# v13 + GQA attention: hoist 16/15 partialSM exps across the post-write barrier into the next QK K-read latency
# baseline (speedup 1.0000x reference)
.Lhoist_gqa_top:
	v_add_f32_e32 v160, 0, v161
	v_add_f32_e32 v160, v175, v160
	s_waitcnt lgkmcnt(3)
	v_mfma_f32_32x32x16_bf16 v[80:95], v[64:67], v[96:99], 0
	v_add_f32_e32 v160, v162, v160
	v_add_f32_e32 v160, v235, v160
	v_add_f32_e32 v160, v174, v160
	v_add_f32_e32 v160, v238, v160
	v_add_f32_e32 v160, v163, v160
	v_add_f32_e32 v160, v173, v160
	v_add_f32_e32 v160, v169, v160
	s_waitcnt lgkmcnt(2)
	v_mfma_f32_32x32x16_bf16 v[64:79], v[68:71], v[96:99], 0
	v_add_f32_e32 v160, v171, v160
	v_add_f32_e32 v160, v170, v160
	v_add_f32_e32 v160, v172, v160
	v_exp_f32_e32 v158, v158
	v_add_f32_e32 v160, v165, v160
	v_exp_f32_e32 v159, v159
	v_add_f32_e32 v160, v167, v160
	s_waitcnt lgkmcnt(1)
	v_mfma_f32_32x32x16_bf16 v[80:95], v[240:243], v[100:103], v[80:95]
	v_exp_f32_e32 v156, v156
	v_add_f32_e32 v160, v166, v160
	v_exp_f32_e32 v157, v157
	v_add_f32_e32 v160, v168, v160
	v_exp_f32_e32 v152, v152
	v_add_f32_e32 v160, v158, v160
	v_exp_f32_e32 v153, v153
	s_waitcnt lgkmcnt(0)
	v_mfma_f32_32x32x16_bf16 v[64:79], v[244:247], v[100:103], v[64:79]
	ds_read_b128 v[240:243], v226 offset:49152
	ds_read_b128 v[244:247], v226 offset:57344
	v_add_f32_e32 v160, v159, v160
	v_exp_f32_e32 v148, v148
	v_add_f32_e32 v160, v156, v160
	v_exp_f32_e32 v149, v149
	v_add_f32_e32 v160, v157, v160
	v_exp_f32_e32 v146, v146
	s_waitcnt lgkmcnt(1)
	v_mfma_f32_32x32x16_bf16 v[80:95], v[240:243], v[104:107], v[80:95]
	v_add_f32_e32 v160, v152, v160
	v_exp_f32_e32 v147, v147
	v_add_f32_e32 v160, v153, v160
	v_exp_f32_e32 v154, v154
	v_add_f32_e32 v160, v148, v160
	v_exp_f32_e32 v155, v155
	v_add_f32_e32 v160, v149, v160
	s_waitcnt lgkmcnt(0)
	v_mfma_f32_32x32x16_bf16 v[64:79], v[244:247], v[104:107], v[64:79]
	ds_read_b128 v[240:243], v225 offset:49152
	ds_read_b128 v[244:247], v225 offset:57344
	v_exp_f32_e32 v150, v150
	v_add_f32_e32 v160, v146, v160
	v_exp_f32_e32 v151, v151
	v_add_f32_e32 v160, v147, v160
	v_exp_f32_e32 v144, v144
	v_add_f32_e32 v160, v154, v160
	s_waitcnt lgkmcnt(1)
	v_mfma_f32_32x32x16_bf16 v[80:95], v[240:243], v[108:111], v[80:95]
	v_exp_f32_e32 v145, v145
	v_add_f32_e32 v160, v155, v160
	v_add_f32_e32 v160, v150, v160
	v_add_f32_e32 v160, v151, v160
	v_add_f32_e32 v160, v144, v160
	v_add_f32_e32 v232, v145, v160
	v_mov_b32_e32 v233, v232
	s_waitcnt lgkmcnt(0)
	v_mfma_f32_32x32x16_bf16 v[64:79], v[244:247], v[108:111], v[64:79]
	ds_read_b128 v[240:243], v227 offset:49152
	ds_read_b128 v[244:247], v227 offset:57344
	v_permlane32_swap_b32_e32 v232, v233
	s_waitcnt lgkmcnt(1)
	v_mfma_f32_32x32x16_bf16 v[80:95], v[240:243], v[112:115], v[80:95]
	s_waitcnt lgkmcnt(0)
	v_mfma_f32_32x32x16_bf16 v[64:79], v[244:247], v[112:115], v[64:79]
	ds_read_b128 v[240:243], v229 offset:49152
	ds_read_b128 v[244:247], v229 offset:57344
	s_waitcnt lgkmcnt(1)
	v_mfma_f32_32x32x16_bf16 v[80:95], v[240:243], v[116:119], v[80:95]
	s_waitcnt lgkmcnt(0)
	v_mfma_f32_32x32x16_bf16 v[64:79], v[244:247], v[116:119], v[64:79]
	ds_read_b128 v[240:243], v228 offset:49152
	ds_read_b128 v[244:247], v228 offset:57344
	s_waitcnt lgkmcnt(1)
	v_mfma_f32_32x32x16_bf16 v[80:95], v[240:243], v[120:123], v[80:95]
	s_waitcnt lgkmcnt(0)
	v_mfma_f32_32x32x16_bf16 v[64:79], v[244:247], v[120:123], v[64:79]
	ds_read_b128 v[240:243], v230 offset:49152
	ds_read_b128 v[244:247], v230 offset:57344
	v_cvt_pk_bf16_f32 v160, v161, v175
	v_cvt_pk_bf16_f32 v161, v162, v235
	v_cvt_pk_bf16_f32 v162, v174, v238
	v_cvt_pk_bf16_f32 v163, v163, v173
	v_cvt_pk_bf16_f32 v234, v169, v171
	v_cvt_pk_bf16_f32 v235, v170, v172
	s_waitcnt lgkmcnt(1)
	v_mfma_f32_32x32x16_bf16 v[80:95], v[240:243], v[124:127], v[80:95]
	v_cvt_pk_bf16_f32 v236, v165, v167
	v_permlane32_swap_b32_e32 v160, v162
	v_cvt_pk_bf16_f32 v237, v166, v168
	v_permlane32_swap_b32_e32 v234, v236
	v_cvt_pk_bf16_f32 v166, v158, v159
	s_waitcnt lgkmcnt(0)
	v_mfma_f32_32x32x16_bf16 v[64:79], v[244:247], v[124:127], v[64:79]
	v_cvt_pk_bf16_f32 v167, v156, v157
	v_cvt_pk_bf16_f32 v168, v152, v153
	v_cvt_pk_bf16_f32 v169, v148, v149
	v_cvt_pk_bf16_f32 v170, v146, v147
	v_cvt_pk_bf16_f32 v171, v154, v155
	v_cvt_pk_bf16_f32 v172, v150, v151
	v_cvt_pk_bf16_f32 v173, v144, v145
	v_permlane32_swap_b32_e32 v161, v163
	v_permlane32_swap_b32_e32 v235, v237
	v_permlane32_swap_b32_e32 v166, v168
	v_permlane32_swap_b32_e32 v167, v169
	v_permlane32_swap_b32_e32 v170, v172
	v_permlane32_swap_b32_e32 v171, v173
	v_add_co_u32_e32 v144, vcc, s33, v188
	s_nop 1
	v_addc_co_u32_e32 v145, vcc, -1, v189, vcc
	v_add_co_u32_e32 v148, vcc, s70, v188
	s_nop 1
	v_addc_co_u32_e32 v149, vcc, -1, v189, vcc
	v_add_co_u32_e32 v152, vcc, s71, v188
	global_load_dwordx4 v[144:147], v[144:145], off
	s_nop 0
	global_load_dwordx4 v[148:151], v[148:149], off
	v_addc_co_u32_e32 v153, vcc, -1, v189, vcc
	v_add_co_u32_e32 v156, vcc, s72, v188
	s_nop 1
	v_addc_co_u32_e32 v157, vcc, -1, v189, vcc
	global_load_dwordx4 v[152:155], v[152:153], off
	s_nop 0
	global_load_dwordx4 v[156:159], v[156:157], off
	ds_read_b64_tr_b16 v[238:239], v203 offset:0
	ds_read_b64_tr_b16 v[240:241], v203 offset:0x800
	ds_read_b64_tr_b16 v[242:243], v203 offset:0x1000
	ds_read_b64_tr_b16 v[244:245], v203 offset:0x1800
	ds_read_b64_tr_b16 v[246:247], v203 offset:0x2000
	ds_read_b64_tr_b16 v[248:249], v203 offset:0x2800
	ds_read_b64_tr_b16 v[180:181], v203 offset:0x3000
	ds_read_b64_tr_b16 v[182:183], v203 offset:0x3800
	s_nop 0
	s_waitcnt lgkmcnt(6)
	v_mfma_f32_32x32x16_bf16 v[0:15], v[160:163], v[238:241], v[0:15]
	s_waitcnt lgkmcnt(4)
	v_mfma_f32_32x32x16_bf16 v[0:15], v[234:237], v[242:245], v[0:15]
	s_waitcnt lgkmcnt(2)
	v_mfma_f32_32x32x16_bf16 v[0:15], v[166:169], v[246:249], v[0:15]
	s_waitcnt lgkmcnt(0)
	v_mfma_f32_32x32x16_bf16 v[0:15], v[170:173], v[180:183], v[0:15]
	ds_read_b64_tr_b16 v[180:181], v203 offset:0x200
	ds_read_b64_tr_b16 v[182:183], v203 offset:0xa00
	ds_read_b64_tr_b16 v[238:239], v203 offset:0x1200
	ds_read_b64_tr_b16 v[240:241], v203 offset:0x1a00
	ds_read_b64_tr_b16 v[242:243], v203 offset:0x2200
	ds_read_b64_tr_b16 v[244:245], v203 offset:0x2a00
	ds_read_b64_tr_b16 v[246:247], v203 offset:0x3200
	ds_read_b64_tr_b16 v[248:249], v203 offset:0x3a00
	s_nop 0
	s_waitcnt lgkmcnt(6)
	v_mfma_f32_32x32x16_bf16 v[48:63], v[160:163], v[180:183], v[48:63]
	ds_read_b64_tr_b16 v[180:181], v203 offset:0x400
	ds_read_b64_tr_b16 v[182:183], v203 offset:0xc00
	s_waitcnt lgkmcnt(6)
	v_mfma_f32_32x32x16_bf16 v[48:63], v[234:237], v[238:241], v[48:63]
	ds_read_b64_tr_b16 v[238:239], v203 offset:0x1400
	ds_read_b64_tr_b16 v[240:241], v203 offset:0x1c00
	s_waitcnt lgkmcnt(6)
	v_mfma_f32_32x32x16_bf16 v[48:63], v[166:169], v[242:245], v[48:63]
	ds_read_b64_tr_b16 v[242:243], v203 offset:0x2400
	ds_read_b64_tr_b16 v[244:245], v203 offset:0x2c00
	s_waitcnt lgkmcnt(6)
	v_mfma_f32_32x32x16_bf16 v[48:63], v[170:173], v[246:249], v[48:63]
	ds_read_b64_tr_b16 v[246:247], v203 offset:0x3400
	ds_read_b64_tr_b16 v[248:249], v203 offset:0x3c00
	s_waitcnt lgkmcnt(6)
	v_mfma_f32_32x32x16_bf16 v[32:47], v[160:163], v[180:183], v[32:47]
	ds_read_b64_tr_b16 v[180:181], v203 offset:0x600
	ds_read_b64_tr_b16 v[182:183], v203 offset:0xe00
	s_waitcnt lgkmcnt(6)
	v_mfma_f32_32x32x16_bf16 v[32:47], v[234:237], v[238:241], v[32:47]
	ds_read_b64_tr_b16 v[238:239], v203 offset:0x1600
	ds_read_b64_tr_b16 v[240:241], v203 offset:0x1e00
	s_waitcnt lgkmcnt(6)
	v_mfma_f32_32x32x16_bf16 v[32:47], v[166:169], v[242:245], v[32:47]
	ds_read_b64_tr_b16 v[242:243], v203 offset:0x2600
	ds_read_b64_tr_b16 v[244:245], v203 offset:0x2e00
	s_waitcnt lgkmcnt(6)
	v_mfma_f32_32x32x16_bf16 v[32:47], v[170:173], v[246:249], v[32:47]
	ds_read_b64_tr_b16 v[246:247], v203 offset:0x3600
	ds_read_b64_tr_b16 v[248:249], v203 offset:0x3e00
	s_waitcnt lgkmcnt(6)
	v_mfma_f32_32x32x16_bf16 v[16:31], v[160:163], v[180:183], v[16:31]
	v_max_f32_e32 v160, v81, v81
	v_max_f32_e32 v161, v80, v80
	v_max_f32_e32 v160, v161, v160
	v_max3_f32 v160, v160, v82, v83
	v_max3_f32 v160, v160, v84, v85
	v_max3_f32 v160, v160, v86, v87
	v_max3_f32 v160, v160, v88, v89
	v_max3_f32 v160, v160, v90, v91
	v_max3_f32 v160, v160, v92, v93
	s_waitcnt lgkmcnt(4)
	v_mfma_f32_32x32x16_bf16 v[16:31], v[234:237], v[238:241], v[16:31]
	v_max3_f32 v160, v160, v94, v95
	v_max3_f32 v160, v160, v64, v65
	v_max3_f32 v160, v160, v66, v67
	v_max3_f32 v160, v160, v68, v69
	v_max3_f32 v160, v160, v70, v71
	v_max3_f32 v160, v160, v72, v73
	v_max3_f32 v160, v160, v74, v75
	v_max3_f32 v160, v160, v76, v77
	s_waitcnt lgkmcnt(2)
	v_mfma_f32_32x32x16_bf16 v[16:31], v[166:169], v[242:245], v[16:31]
	v_max3_f32 v160, v160, v78, v79
	v_mov_b32_e32 v161, v160
	s_nop 1
	v_permlane32_swap_b32_e32 v160, v161
	v_max_f32_e32 v161, v161, v161
	v_max_f32_e32 v160, v160, v160
	v_max_f32_e32 v160, v160, v161
	v_sub_f32_e32 v161, v160, v164
	v_cmp_ge_f32_e32 vcc, s69, v161
	v_max_f32_e32 v161, v164, v164
	v_max_f32_e32 v160, v161, v160
	s_waitcnt lgkmcnt(0)
	v_mfma_f32_32x32x16_bf16 v[16:31], v[170:173], v[246:249], v[16:31]
	v_sub_f32_e32 v161, v164, v160
	v_mul_f32_e32 v161, 0x3e0293ee, v161
	v_exp_f32_e32 v161, v161
	s_cmp_eq_u64 vcc, exec
	s_cselect_b64 s[0:1], -1, 0
	s_barrier
	s_waitcnt vmcnt(4)
	v_cndmask_b32_e64 v234, v161, 1.0, s[0:1]
	v_cmp_gt_f32_e32 vcc, 1.0, v234
	s_waitcnt vmcnt(7)
	ds_write_b128 v207, v[128:131]
	s_waitcnt vmcnt(6)
	ds_write_b128 v208, v[136:139]
	s_waitcnt vmcnt(5)
	ds_write_b128 v205, v[132:135] offset:32768
	s_waitcnt vmcnt(4)
	ds_write_b128 v206, v[140:143] offset:32768
	s_cbranch_vccz .LBB0_662
	s_and_saveexec_b64 s[24:25], s[6:7]
	ds_write_b32 v200, v234 offset:128
	s_or_b64 exec, exec, s[24:25]
	s_waitcnt lgkmcnt(0)
	v_add_u32_e32 v161, v187, v178
	ds_read_b128 v[166:169], v161 offset:224
	ds_read_b128 v[170:173], v161 offset:192
	ds_read_b128 v[180:183], v161 offset:160
	ds_read_b128 v[236:239], v161 offset:128
	s_waitcnt lgkmcnt(3)
	v_pk_mul_f32 v[12:13], v[12:13], v[166:167]
	s_waitcnt lgkmcnt(2)
	v_pk_mul_f32 v[8:9], v[8:9], v[170:171]
	s_waitcnt lgkmcnt(1)
	v_pk_mul_f32 v[4:5], v[4:5], v[180:181]
	v_pk_mul_f32 v[14:15], v[14:15], v[168:169]
	v_pk_mul_f32 v[10:11], v[10:11], v[172:173]
	v_pk_mul_f32 v[6:7], v[6:7], v[182:183]
	s_waitcnt lgkmcnt(0)
	v_pk_mul_f32 v[2:3], v[2:3], v[238:239]
	v_pk_mul_f32 v[0:1], v[0:1], v[236:237]
	v_pk_mul_f32 v[60:61], v[60:61], v[166:167]
	v_pk_mul_f32 v[56:57], v[56:57], v[170:171]
	v_pk_mul_f32 v[52:53], v[52:53], v[180:181]
	v_pk_mul_f32 v[62:63], v[62:63], v[168:169]
	v_pk_mul_f32 v[58:59], v[58:59], v[172:173]
	v_pk_mul_f32 v[54:55], v[54:55], v[182:183]
	v_pk_mul_f32 v[50:51], v[50:51], v[238:239]
	v_pk_mul_f32 v[48:49], v[48:49], v[236:237]
	v_pk_mul_f32 v[44:45], v[44:45], v[166:167]
	v_pk_mul_f32 v[40:41], v[40:41], v[170:171]
	v_pk_mul_f32 v[36:37], v[36:37], v[180:181]
	v_pk_mul_f32 v[46:47], v[46:47], v[168:169]
	v_pk_mul_f32 v[42:43], v[42:43], v[172:173]
	v_pk_mul_f32 v[38:39], v[38:39], v[182:183]
	v_pk_mul_f32 v[34:35], v[34:35], v[238:239]
	v_pk_mul_f32 v[32:33], v[32:33], v[236:237]
	v_pk_mul_f32 v[28:29], v[28:29], v[166:167]
	v_pk_mul_f32 v[24:25], v[24:25], v[170:171]
	v_pk_mul_f32 v[20:21], v[20:21], v[180:181]
	v_pk_mul_f32 v[30:31], v[30:31], v[168:169]
	v_pk_mul_f32 v[26:27], v[26:27], v[172:173]
	v_pk_mul_f32 v[22:23], v[22:23], v[182:183]
	v_pk_mul_f32 v[18:19], v[18:19], v[238:239]
	v_pk_mul_f32 v[16:17], v[16:17], v[236:237]
.LBB0_662:
	v_cndmask_b32_e64 v235, v160, v164, s[0:1]
	v_mul_f32_e32 v236, 0xbe0293ee, v235
	v_fmamk_f32 v80, v80, 0x3e0293ee, v236
	v_fmamk_f32 v81, v81, 0x3e0293ee, v236
	v_fmamk_f32 v82, v82, 0x3e0293ee, v236
	v_fmamk_f32 v83, v83, 0x3e0293ee, v236
	v_fmamk_f32 v84, v84, 0x3e0293ee, v236
	v_fmamk_f32 v85, v85, 0x3e0293ee, v236
	v_fmamk_f32 v86, v86, 0x3e0293ee, v236
	v_fmamk_f32 v87, v87, 0x3e0293ee, v236
	v_fmamk_f32 v88, v88, 0x3e0293ee, v236
	v_fmamk_f32 v89, v89, 0x3e0293ee, v236
	v_fmamk_f32 v90, v90, 0x3e0293ee, v236
	v_fmamk_f32 v91, v91, 0x3e0293ee, v236
	v_fmamk_f32 v92, v92, 0x3e0293ee, v236
	v_fmamk_f32 v93, v93, 0x3e0293ee, v236
	v_fmamk_f32 v94, v94, 0x3e0293ee, v236
	v_fmamk_f32 v95, v95, 0x3e0293ee, v236
	v_fmamk_f32 v245, v64, 0x3e0293ee, v236
	v_fmamk_f32 v246, v65, 0x3e0293ee, v236
	v_fmamk_f32 v247, v66, 0x3e0293ee, v236
	v_fmamk_f32 v248, v67, 0x3e0293ee, v236
	v_fmamk_f32 v249, v68, 0x3e0293ee, v236
	v_fmamk_f32 v238, v69, 0x3e0293ee, v236
	v_fmamk_f32 v239, v70, 0x3e0293ee, v236
	v_fmamk_f32 v240, v71, 0x3e0293ee, v236
	v_fmamk_f32 v241, v72, 0x3e0293ee, v236
	v_fmamk_f32 v242, v73, 0x3e0293ee, v236
	v_fmamk_f32 v243, v74, 0x3e0293ee, v236
	v_fmamk_f32 v244, v75, 0x3e0293ee, v236
	v_fmamk_f32 v237, v76, 0x3e0293ee, v236
	v_fmamk_f32 v250, v77, 0x3e0293ee, v236
	v_fmamk_f32 v251, v78, 0x3e0293ee, v236
	v_fmac_f32_e32 v236, 0x3e0293ee, v79
	s_waitcnt lgkmcnt(0)
	s_barrier
	ds_read_b128 v[64:67], v204 offset:32768
	ds_read_b128 v[68:71], v204 offset:40960
	ds_read_b128 v[180:183], v209 offset:32768
	ds_read_b128 v[210:213], v209 offset:40960
	v_exp_f32_e32 v160, v80
	v_exp_f32_e32 v175, v81
	v_exp_f32_e32 v161, v82
	v_exp_f32_e32 v174, v83
	v_exp_f32_e32 v162, v84
	v_exp_f32_e32 v173, v85
	v_exp_f32_e32 v163, v86
	v_exp_f32_e32 v172, v87
	v_exp_f32_e32 v164, v88
	v_exp_f32_e32 v171, v89
	v_exp_f32_e32 v165, v90
	v_exp_f32_e32 v170, v91
	v_exp_f32_e32 v166, v92
	v_exp_f32_e32 v169, v93
	v_exp_f32_e32 v167, v94
	v_exp_f32_e32 v168, v95
	s_waitcnt lgkmcnt(3)
	v_mfma_f32_32x32x16_bf16 v[80:95], v[64:67], v[96:99], 0
	s_waitcnt lgkmcnt(2)
	v_mfma_f32_32x32x16_bf16 v[64:79], v[68:71], v[96:99], 0
	s_waitcnt lgkmcnt(1)
	v_mfma_f32_32x32x16_bf16 v[80:95], v[180:183], v[100:103], v[80:95]
	s_waitcnt lgkmcnt(0)
	v_mfma_f32_32x32x16_bf16 v[64:79], v[210:213], v[100:103], v[64:79]
	ds_read_b128 v[180:183], v226 offset:32768
	ds_read_b128 v[210:213], v226 offset:40960
	s_waitcnt lgkmcnt(1)
	v_mfma_f32_32x32x16_bf16 v[80:95], v[180:183], v[104:107], v[80:95]
	s_waitcnt lgkmcnt(0)
	v_mfma_f32_32x32x16_bf16 v[64:79], v[210:213], v[104:107], v[64:79]
	ds_read_b128 v[180:183], v225 offset:32768
	ds_read_b128 v[210:213], v225 offset:40960
	s_waitcnt lgkmcnt(1)
	v_mfma_f32_32x32x16_bf16 v[80:95], v[180:183], v[108:111], v[80:95]
	s_waitcnt lgkmcnt(0)
	v_mfma_f32_32x32x16_bf16 v[64:79], v[210:213], v[108:111], v[64:79]
	ds_read_b128 v[180:183], v227 offset:32768
	ds_read_b128 v[210:213], v227 offset:40960
	s_waitcnt lgkmcnt(1)
	v_mfma_f32_32x32x16_bf16 v[80:95], v[180:183], v[112:115], v[80:95]
	s_waitcnt lgkmcnt(0)
	v_mfma_f32_32x32x16_bf16 v[64:79], v[210:213], v[112:115], v[64:79]
	ds_read_b128 v[180:183], v229 offset:32768
	ds_read_b128 v[210:213], v229 offset:40960
	s_waitcnt lgkmcnt(1)
	v_mfma_f32_32x32x16_bf16 v[80:95], v[180:183], v[116:119], v[80:95]
	s_waitcnt lgkmcnt(0)
	v_mfma_f32_32x32x16_bf16 v[64:79], v[210:213], v[116:119], v[64:79]
	ds_read_b128 v[180:183], v228 offset:32768
	ds_read_b128 v[210:213], v228 offset:40960
	s_waitcnt lgkmcnt(1)
	v_mfma_f32_32x32x16_bf16 v[80:95], v[180:183], v[120:123], v[80:95]
	s_waitcnt lgkmcnt(0)
	v_mfma_f32_32x32x16_bf16 v[64:79], v[210:213], v[120:123], v[64:79]
	ds_read_b128 v[180:183], v230 offset:32768
	ds_read_b128 v[210:213], v230 offset:40960
	s_waitcnt lgkmcnt(1)
	v_mfma_f32_32x32x16_bf16 v[80:95], v[180:183], v[124:127], v[80:95]
	v_exp_f32_e32 v180, v245
	v_exp_f32_e32 v245, v236
	v_add_f32_e32 v236, 0, v160
	v_add_f32_e32 v236, v175, v236
	v_add_f32_e32 v236, v161, v236
	v_add_f32_e32 v236, v174, v236
	v_add_f32_e32 v236, v162, v236
	v_add_f32_e32 v236, v173, v236
	v_add_f32_e32 v236, v163, v236
	v_add_f32_e32 v236, v172, v236
	v_add_f32_e32 v236, v164, v236
	v_add_f32_e32 v236, v171, v236
	v_add_f32_e32 v236, v165, v236
	v_add_f32_e32 v236, v170, v236
	v_add_f32_e32 v236, v166, v236
	v_exp_f32_e32 v181, v246
	v_add_f32_e32 v236, v169, v236
	v_exp_f32_e32 v182, v247
	v_add_f32_e32 v236, v167, v236
	v_exp_f32_e32 v183, v248
	v_add_f32_e32 v236, v168, v236
	s_waitcnt lgkmcnt(0)
	v_mfma_f32_32x32x16_bf16 v[64:79], v[210:213], v[124:127], v[64:79]
	v_exp_f32_e32 v210, v249
	v_add_f32_e32 v236, v180, v236
	v_exp_f32_e32 v211, v238
	v_add_f32_e32 v236, v181, v236
	v_exp_f32_e32 v212, v239
	v_add_f32_e32 v236, v182, v236
	v_exp_f32_e32 v213, v240
	v_add_f32_e32 v236, v183, v236
	v_exp_f32_e32 v238, v241
	v_add_f32_e32 v236, v210, v236
	v_exp_f32_e32 v239, v242
	v_add_f32_e32 v236, v211, v236
	v_exp_f32_e32 v240, v243
	v_add_f32_e32 v236, v212, v236
	v_exp_f32_e32 v241, v244
	v_add_f32_e32 v236, v213, v236
	v_exp_f32_e32 v242, v237
	v_add_f32_e32 v236, v238, v236
	v_exp_f32_e32 v243, v250
	v_add_f32_e32 v236, v239, v236
	v_exp_f32_e32 v244, v251
	v_add_f32_e32 v236, v240, v236
	v_add_f32_e32 v236, v241, v236
	v_add_f32_e32 v236, v242, v236
	v_add_f32_e32 v236, v243, v236
	v_add_f32_e32 v236, v244, v236
	v_add_f32_e32 v236, v245, v236
	v_mov_b32_e32 v237, v236
	v_cvt_pk_bf16_f32 v160, v160, v175
	v_cvt_pk_bf16_f32 v161, v161, v174
	v_cvt_pk_bf16_f32 v162, v162, v173
	v_cvt_pk_bf16_f32 v163, v163, v172
	v_cvt_pk_bf16_f32 v164, v164, v171
	v_cvt_pk_bf16_f32 v165, v165, v170
	v_cvt_pk_bf16_f32 v166, v166, v169
	v_cvt_pk_bf16_f32 v167, v167, v168
	v_cvt_pk_bf16_f32 v168, v180, v181
	v_cvt_pk_bf16_f32 v169, v182, v183
	v_cvt_pk_bf16_f32 v170, v210, v211
	v_cvt_pk_bf16_f32 v171, v212, v213
	v_cvt_pk_bf16_f32 v172, v238, v239
	v_cvt_pk_bf16_f32 v173, v240, v241
	v_cvt_pk_bf16_f32 v174, v242, v243
	v_cvt_pk_bf16_f32 v175, v244, v245
	s_nop 1
	v_permlane32_swap_b32_e32 v236, v237
	v_permlane32_swap_b32_e32 v160, v162
	v_permlane32_swap_b32_e32 v161, v163
	v_permlane32_swap_b32_e32 v164, v166
	v_permlane32_swap_b32_e32 v165, v167
	v_permlane32_swap_b32_e32 v168, v170
	v_permlane32_swap_b32_e32 v169, v171
	v_permlane32_swap_b32_e32 v172, v174
	v_permlane32_swap_b32_e32 v173, v175
	s_cmp_ge_u32 s35, s30
	s_cselect_b64 s[24:25], -1, 0
	s_and_b64 vcc, exec, s[24:25]
	s_cbranch_vccnz .Latt_noload_gqa
	v_add_co_u32_e32 v128, vcc, 0xffff4000, v188
	s_nop 1
	v_addc_co_u32_e32 v129, vcc, -1, v189, vcc
	v_add_co_u32_e32 v132, vcc, 0xfe6f4000, v188
	s_nop 1
	v_addc_co_u32_e32 v133, vcc, -1, v189, vcc
	v_add_co_u32_e32 v140, vcc, 0xfe700000, v188
	global_load_dwordx4 v[128:131], v[128:129], off
	s_nop 0
	global_load_dwordx4 v[132:135], v[132:133], off
	v_addc_co_u32_e32 v141, vcc, -1, v189, vcc
	global_load_dwordx4 v[136:139], v[188:189], off
	s_nop 0
	global_load_dwordx4 v[140:143], v[140:141], off

.LBB0_668:
	v_cndmask_b32_e64 v164, v161, v235, s[0:1]
	v_mul_f32_e32 v144, 0xbe0293ee, v164
	v_mov_b32_e32 v145, v144
	v_fmamk_f32 v80, v80, 0x3e0293ee, v144
	v_fmamk_f32 v81, v81, 0x3e0293ee, v144
	v_fmamk_f32 v82, v82, 0x3e0293ee, v144
	v_fmamk_f32 v83, v83, 0x3e0293ee, v144
	v_fmamk_f32 v84, v84, 0x3e0293ee, v144
	v_fmamk_f32 v85, v85, 0x3e0293ee, v144
	v_fmamk_f32 v86, v86, 0x3e0293ee, v144
	v_fmamk_f32 v87, v87, 0x3e0293ee, v144
	v_fmamk_f32 v88, v88, 0x3e0293ee, v144
	v_fmamk_f32 v89, v89, 0x3e0293ee, v144
	v_fmamk_f32 v90, v90, 0x3e0293ee, v144
	v_fmamk_f32 v91, v91, 0x3e0293ee, v144
	v_fmamk_f32 v92, v92, 0x3e0293ee, v144
	v_fmamk_f32 v93, v93, 0x3e0293ee, v144
	v_fmamk_f32 v94, v94, 0x3e0293ee, v144
	v_fmac_f32_e32 v145, 0x3e0293ee, v95
	v_exp_f32_e32 v168, v145
	v_pk_fma_f32 v[158:159], v[64:65], s[64:65], v[144:145] op_sel_hi:[1,0,0]
	v_add_f32_e32 v64, v232, v233
	v_fmac_f32_e32 v64, v231, v201
	v_add_f32_e32 v201, v236, v237
	v_pk_fma_f32 v[156:157], v[66:67], s[64:65], v[144:145] op_sel_hi:[1,0,0]
	v_pk_fma_f32 v[152:153], v[68:69], s[64:65], v[144:145] op_sel_hi:[1,0,0]
	v_pk_fma_f32 v[148:149], v[70:71], s[64:65], v[144:145] op_sel_hi:[1,0,0]
	v_pk_fma_f32 v[146:147], v[72:73], s[64:65], v[144:145] op_sel_hi:[1,0,0]
	v_pk_fma_f32 v[154:155], v[74:75], s[64:65], v[144:145] op_sel_hi:[1,0,0]
	v_pk_fma_f32 v[150:151], v[76:77], s[64:65], v[144:145] op_sel_hi:[1,0,0]
	v_pk_fma_f32 v[144:145], v[78:79], s[64:65], v[144:145] op_sel_hi:[1,0,0]
	v_fmac_f32_e32 v201, v64, v234
	s_add_i32 s35, s35, 2
	v_lshl_add_u64 v[188:189], v[188:189], 0, s[66:67]
	s_and_b64 vcc, exec, s[24:25]
	s_waitcnt lgkmcnt(0)
	s_barrier
	s_cbranch_vccnz .LBB0_670
	v_mov_b32_e32 v231, v160
	ds_read_b128 v[64:67], v204 offset:49152
	ds_read_b128 v[68:71], v204 offset:57344
	ds_read_b128 v[240:243], v209 offset:49152
	ds_read_b128 v[244:247], v209 offset:57344
	v_exp_f32_e32 v161, v80
	v_exp_f32_e32 v175, v81
	v_exp_f32_e32 v162, v82
	v_exp_f32_e32 v235, v83
	v_exp_f32_e32 v174, v84
	v_exp_f32_e32 v238, v85
	v_exp_f32_e32 v163, v86
	v_exp_f32_e32 v173, v87
	v_exp_f32_e32 v169, v88
	v_exp_f32_e32 v171, v89
	v_exp_f32_e32 v170, v90
	v_exp_f32_e32 v172, v91
	v_exp_f32_e32 v165, v92
	v_exp_f32_e32 v167, v93
	v_exp_f32_e32 v166, v94
	s_branch .Lhoist_gqa_top

.LBB0_670:
	ds_read_b128 v[64:67], v204 offset:49152
	ds_read_b128 v[68:71], v204 offset:57344
	v_exp_f32_e32 v161, v80
	v_exp_f32_e32 v175, v81
	v_exp_f32_e32 v162, v82
	v_exp_f32_e32 v235, v83
	v_exp_f32_e32 v174, v84
	v_exp_f32_e32 v238, v85
	v_exp_f32_e32 v163, v86
	v_exp_f32_e32 v173, v87
	v_exp_f32_e32 v169, v88
	v_exp_f32_e32 v171, v89
	v_exp_f32_e32 v170, v90
	v_exp_f32_e32 v172, v91
	v_exp_f32_e32 v165, v92
	v_exp_f32_e32 v167, v93
	v_exp_f32_e32 v166, v94
	s_waitcnt lgkmcnt(1)
	v_mfma_f32_32x32x16_bf16 v[80:95], v[64:67], v[96:99], 0
	s_waitcnt lgkmcnt(0)
	v_mfma_f32_32x32x16_bf16 v[64:79], v[68:71], v[96:99], 0
	ds_read_b128 v[96:99], v209 offset:49152
	ds_read_b128 v[128:131], v209 offset:57344
	s_waitcnt lgkmcnt(1)
	v_mfma_f32_32x32x16_bf16 v[80:95], v[96:99], v[100:103], v[80:95]
	s_waitcnt lgkmcnt(0)
	v_mfma_f32_32x32x16_bf16 v[64:79], v[128:131], v[100:103], v[64:79]
	ds_read_b128 v[96:99], v226 offset:49152
	ds_read_b128 v[100:103], v226 offset:57344
	s_waitcnt lgkmcnt(1)
	v_mfma_f32_32x32x16_bf16 v[80:95], v[96:99], v[104:107], v[80:95]
	s_waitcnt lgkmcnt(0)
	v_mfma_f32_32x32x16_bf16 v[64:79], v[100:103], v[104:107], v[64:79]
	ds_read_b128 v[96:99], v225 offset:49152
	ds_read_b128 v[100:103], v225 offset:57344
	v_exp_f32_e32 v106, v158
	v_exp_f32_e32 v107, v159
	s_waitcnt lgkmcnt(1)
	v_mfma_f32_32x32x16_bf16 v[80:95], v[96:99], v[108:111], v[80:95]
	s_waitcnt lgkmcnt(0)
	v_mfma_f32_32x32x16_bf16 v[64:79], v[100:103], v[108:111], v[64:79]
	ds_read_b128 v[96:99], v227 offset:49152
	ds_read_b128 v[100:103], v227 offset:57344
	v_exp_f32_e32 v108, v156
	v_exp_f32_e32 v109, v157
	v_exp_f32_e32 v110, v152
	v_exp_f32_e32 v111, v153
	s_waitcnt lgkmcnt(1)
	v_mfma_f32_32x32x16_bf16 v[80:95], v[96:99], v[112:115], v[80:95]
	s_waitcnt lgkmcnt(0)
	v_mfma_f32_32x32x16_bf16 v[64:79], v[100:103], v[112:115], v[64:79]
	ds_read_b128 v[96:99], v229 offset:49152
	ds_read_b128 v[100:103], v229 offset:57344
	v_exp_f32_e32 v112, v148
	v_exp_f32_e32 v113, v149
	v_exp_f32_e32 v114, v146
	v_exp_f32_e32 v115, v147
	s_waitcnt lgkmcnt(1)
	v_mfma_f32_32x32x16_bf16 v[80:95], v[96:99], v[116:119], v[80:95]
	s_waitcnt lgkmcnt(0)
	v_mfma_f32_32x32x16_bf16 v[64:79], v[100:103], v[116:119], v[64:79]
	ds_read_b128 v[96:99], v228 offset:49152
	ds_read_b128 v[100:103], v228 offset:57344
	v_exp_f32_e32 v116, v154
	v_exp_f32_e32 v117, v155
	v_exp_f32_e32 v118, v150
	v_exp_f32_e32 v119, v151
	s_waitcnt lgkmcnt(1)
	v_mfma_f32_32x32x16_bf16 v[80:95], v[96:99], v[120:123], v[80:95]
	s_waitcnt lgkmcnt(0)
	v_mfma_f32_32x32x16_bf16 v[64:79], v[100:103], v[120:123], v[64:79]
	ds_read_b128 v[96:99], v230 offset:49152
	ds_read_b128 v[100:103], v230 offset:57344
	v_exp_f32_e32 v120, v144
	v_exp_f32_e32 v121, v145
	s_waitcnt lgkmcnt(1)
	v_mfma_f32_32x32x16_bf16 v[80:95], v[96:99], v[124:127], v[80:95]
	v_add_f32_e32 v96, 0, v161
	v_add_f32_e32 v96, v175, v96
	v_add_f32_e32 v96, v162, v96
	v_add_f32_e32 v96, v235, v96
	v_add_f32_e32 v96, v174, v96
	v_add_f32_e32 v96, v238, v96
	v_add_f32_e32 v96, v163, v96
	v_add_f32_e32 v96, v173, v96
	v_add_f32_e32 v96, v169, v96
	v_add_f32_e32 v96, v171, v96
	v_add_f32_e32 v96, v170, v96
	v_add_f32_e32 v96, v172, v96
	v_add_f32_e32 v96, v165, v96
	v_add_f32_e32 v96, v167, v96
	v_add_f32_e32 v96, v166, v96
	v_add_f32_e32 v96, v168, v96
	v_add_f32_e32 v96, v106, v96
	v_add_f32_e32 v96, v107, v96
	v_add_f32_e32 v96, v108, v96
	v_add_f32_e32 v96, v109, v96
	v_add_f32_e32 v96, v110, v96
	v_add_f32_e32 v96, v111, v96
	v_add_f32_e32 v96, v112, v96
	v_add_f32_e32 v96, v113, v96
	v_add_f32_e32 v96, v114, v96
	v_add_f32_e32 v96, v115, v96
	s_waitcnt lgkmcnt(0)
	v_mfma_f32_32x32x16_bf16 v[64:79], v[100:103], v[124:127], v[64:79]
	v_add_f32_e32 v96, v116, v96
	v_add_f32_e32 v96, v117, v96
	v_add_f32_e32 v96, v118, v96
	v_add_f32_e32 v96, v119, v96
	v_add_f32_e32 v96, v120, v96
	v_add_f32_e32 v100, v121, v96
	v_mov_b32_e32 v101, v100
	v_cvt_pk_bf16_f32 v96, v161, v175
	v_cvt_pk_bf16_f32 v97, v162, v235
	v_cvt_pk_bf16_f32 v98, v174, v238
	v_cvt_pk_bf16_f32 v99, v163, v173
	s_nop 1
	v_permlane32_swap_b32_e32 v100, v101
	v_permlane32_swap_b32_e32 v96, v98
	v_permlane32_swap_b32_e32 v97, v99
	v_cvt_pk_bf16_f32 v102, v169, v171
	v_cvt_pk_bf16_f32 v103, v170, v172
	v_cvt_pk_bf16_f32 v104, v165, v167
	v_cvt_pk_bf16_f32 v105, v166, v168
	v_cvt_pk_bf16_f32 v106, v106, v107
	v_cvt_pk_bf16_f32 v107, v108, v109
	v_cvt_pk_bf16_f32 v108, v110, v111
	v_cvt_pk_bf16_f32 v109, v112, v113
	v_cvt_pk_bf16_f32 v110, v114, v115
	v_cvt_pk_bf16_f32 v111, v116, v117
	v_cvt_pk_bf16_f32 v112, v118, v119
	v_cvt_pk_bf16_f32 v113, v120, v121
	s_nop 0
	v_permlane32_swap_b32_e32 v102, v104
	v_permlane32_swap_b32_e32 v103, v105
	v_permlane32_swap_b32_e32 v106, v108
	v_permlane32_swap_b32_e32 v107, v109
	v_permlane32_swap_b32_e32 v110, v112
	v_permlane32_swap_b32_e32 v111, v113
	ds_read_b64_tr_b16 v[114:115], v203 offset:0
	ds_read_b64_tr_b16 v[116:117], v203 offset:0x800
	ds_read_b64_tr_b16 v[118:119], v203 offset:0x1000
	ds_read_b64_tr_b16 v[120:121], v203 offset:0x1800
	ds_read_b64_tr_b16 v[122:123], v203 offset:0x2000
	ds_read_b64_tr_b16 v[124:125], v203 offset:0x2800
	ds_read_b64_tr_b16 v[126:127], v203 offset:0x3000
	ds_read_b64_tr_b16 v[128:129], v203 offset:0x3800
	s_nop 0
	s_waitcnt lgkmcnt(6)
	v_mfma_f32_32x32x16_bf16 v[0:15], v[96:99], v[114:117], v[0:15]
	ds_read_b64_tr_b16 v[114:115], v203 offset:0x200
	ds_read_b64_tr_b16 v[116:117], v203 offset:0xa00
	s_waitcnt lgkmcnt(6)
	v_mfma_f32_32x32x16_bf16 v[0:15], v[102:105], v[118:121], v[0:15]
	ds_read_b64_tr_b16 v[118:119], v203 offset:0x1200
	ds_read_b64_tr_b16 v[120:121], v203 offset:0x1a00
	s_waitcnt lgkmcnt(6)
	v_mfma_f32_32x32x16_bf16 v[0:15], v[106:109], v[122:125], v[0:15]
	ds_read_b64_tr_b16 v[122:123], v203 offset:0x2200
	ds_read_b64_tr_b16 v[124:125], v203 offset:0x2a00
	s_waitcnt lgkmcnt(6)
	v_mfma_f32_32x32x16_bf16 v[0:15], v[110:113], v[126:129], v[0:15]
	ds_read_b64_tr_b16 v[126:127], v203 offset:0x3200
	ds_read_b64_tr_b16 v[128:129], v203 offset:0x3a00
	s_waitcnt lgkmcnt(6)
	v_mfma_f32_32x32x16_bf16 v[48:63], v[96:99], v[114:117], v[48:63]
	ds_read_b64_tr_b16 v[114:115], v203 offset:0x400
	ds_read_b64_tr_b16 v[116:117], v203 offset:0xc00
	s_waitcnt lgkmcnt(6)
	v_mfma_f32_32x32x16_bf16 v[48:63], v[102:105], v[118:121], v[48:63]
	ds_read_b64_tr_b16 v[118:119], v203 offset:0x1400
	ds_read_b64_tr_b16 v[120:121], v203 offset:0x1c00
	s_waitcnt lgkmcnt(6)
	v_mfma_f32_32x32x16_bf16 v[48:63], v[106:109], v[122:125], v[48:63]
	ds_read_b64_tr_b16 v[122:123], v203 offset:0x2400
	ds_read_b64_tr_b16 v[124:125], v203 offset:0x2c00
	s_waitcnt lgkmcnt(6)
	v_mfma_f32_32x32x16_bf16 v[48:63], v[110:113], v[126:129], v[48:63]
	ds_read_b64_tr_b16 v[126:127], v203 offset:0x3400
	ds_read_b64_tr_b16 v[128:129], v203 offset:0x3c00
	s_waitcnt lgkmcnt(6)
	v_mfma_f32_32x32x16_bf16 v[32:47], v[96:99], v[114:117], v[32:47]
	ds_read_b64_tr_b16 v[114:115], v203 offset:0x600
	ds_read_b64_tr_b16 v[116:117], v203 offset:0xe00
	s_waitcnt lgkmcnt(6)
	v_mfma_f32_32x32x16_bf16 v[32:47], v[102:105], v[118:121], v[32:47]
	ds_read_b64_tr_b16 v[118:119], v203 offset:0x1600
	ds_read_b64_tr_b16 v[120:121], v203 offset:0x1e00
	s_waitcnt lgkmcnt(6)
	v_mfma_f32_32x32x16_bf16 v[32:47], v[106:109], v[122:125], v[32:47]
	ds_read_b64_tr_b16 v[122:123], v203 offset:0x2600
	ds_read_b64_tr_b16 v[124:125], v203 offset:0x2e00
	s_waitcnt lgkmcnt(6)
	v_mfma_f32_32x32x16_bf16 v[32:47], v[110:113], v[126:129], v[32:47]
	ds_read_b64_tr_b16 v[126:127], v203 offset:0x3600
	ds_read_b64_tr_b16 v[128:129], v203 offset:0x3e00
	s_waitcnt lgkmcnt(6)
	v_mfma_f32_32x32x16_bf16 v[16:31], v[96:99], v[114:117], v[16:31]
	v_max_f32_e32 v96, v81, v81
	v_max_f32_e32 v97, v80, v80
	v_max_f32_e32 v96, v97, v96
	v_max3_f32 v96, v96, v82, v83
	v_max3_f32 v96, v96, v84, v85
	v_max3_f32 v96, v96, v86, v87
	v_max3_f32 v96, v96, v88, v89
	v_max3_f32 v96, v96, v90, v91
	v_max3_f32 v96, v96, v92, v93
	s_waitcnt lgkmcnt(4)
	v_mfma_f32_32x32x16_bf16 v[16:31], v[102:105], v[118:121], v[16:31]
	v_max3_f32 v96, v96, v94, v95
	v_max3_f32 v96, v96, v64, v65
	v_max3_f32 v96, v96, v66, v67
	v_max3_f32 v96, v96, v68, v69
	v_max3_f32 v96, v96, v70, v71
	v_max3_f32 v96, v96, v72, v73
	v_max3_f32 v96, v96, v74, v75
	v_max3_f32 v96, v96, v76, v77
	s_waitcnt lgkmcnt(2)
	v_mfma_f32_32x32x16_bf16 v[16:31], v[106:109], v[122:125], v[16:31]
	v_max3_f32 v96, v96, v78, v79
	v_mov_b32_e32 v97, v96
	s_nop 1
	v_permlane32_swap_b32_e32 v96, v97
	v_max_f32_e32 v97, v97, v97
	v_max_f32_e32 v96, v96, v96
	v_max_f32_e32 v96, v96, v97
	v_sub_f32_e32 v97, v96, v164
	v_cmp_ge_f32_e32 vcc, s69, v97
	v_max_f32_e32 v97, v164, v164
	v_max_f32_e32 v97, v97, v96
	s_waitcnt lgkmcnt(0)
	v_mfma_f32_32x32x16_bf16 v[16:31], v[110:113], v[126:129], v[16:31]
	v_sub_f32_e32 v96, v164, v97
	v_mul_f32_e32 v96, 0x3e0293ee, v96
	v_exp_f32_e32 v96, v96
	s_cmp_eq_u64 vcc, exec
	s_cselect_b64 s[0:1], -1, 0
	v_cndmask_b32_e64 v96, v96, 1.0, s[0:1]
	v_cmp_gt_f32_e32 vcc, 1.0, v96
	s_barrier
	s_cbranch_vccz .LBB0_674
	s_and_saveexec_b64 s[24:25], s[6:7]
	ds_write_b32 v200, v96 offset:128
	s_or_b64 exec, exec, s[24:25]
	s_waitcnt lgkmcnt(0)
	v_add_u32_e32 v98, v187, v178
	ds_read_b128 v[102:105], v98 offset:224
	ds_read_b128 v[106:109], v98 offset:192
	ds_read_b128 v[110:113], v98 offset:160
	ds_read_b128 v[114:117], v98 offset:128
	s_waitcnt lgkmcnt(3)
	v_pk_mul_f32 v[12:13], v[12:13], v[102:103]
	s_waitcnt lgkmcnt(2)
	v_pk_mul_f32 v[8:9], v[8:9], v[106:107]
	s_waitcnt lgkmcnt(1)
	v_pk_mul_f32 v[4:5], v[4:5], v[110:111]
	v_pk_mul_f32 v[14:15], v[14:15], v[104:105]
	v_pk_mul_f32 v[10:11], v[10:11], v[108:109]
	v_pk_mul_f32 v[6:7], v[6:7], v[112:113]
	s_waitcnt lgkmcnt(0)
	v_pk_mul_f32 v[2:3], v[2:3], v[116:117]
	v_pk_mul_f32 v[0:1], v[0:1], v[114:115]
	v_pk_mul_f32 v[60:61], v[60:61], v[102:103]
	v_pk_mul_f32 v[56:57], v[56:57], v[106:107]
	v_pk_mul_f32 v[52:53], v[52:53], v[110:111]
	v_pk_mul_f32 v[62:63], v[62:63], v[104:105]
	v_pk_mul_f32 v[58:59], v[58:59], v[108:109]
	v_pk_mul_f32 v[54:55], v[54:55], v[112:113]
	v_pk_mul_f32 v[50:51], v[50:51], v[116:117]
	v_pk_mul_f32 v[48:49], v[48:49], v[114:115]
	v_pk_mul_f32 v[44:45], v[44:45], v[102:103]
	v_pk_mul_f32 v[40:41], v[40:41], v[106:107]
	v_pk_mul_f32 v[36:37], v[36:37], v[110:111]
	v_pk_mul_f32 v[46:47], v[46:47], v[104:105]
	v_pk_mul_f32 v[42:43], v[42:43], v[108:109]
	v_pk_mul_f32 v[38:39], v[38:39], v[112:113]
	v_pk_mul_f32 v[34:35], v[34:35], v[116:117]
	v_pk_mul_f32 v[32:33], v[32:33], v[114:115]
	v_pk_mul_f32 v[28:29], v[28:29], v[102:103]
	v_pk_mul_f32 v[24:25], v[24:25], v[106:107]
	v_pk_mul_f32 v[20:21], v[20:21], v[110:111]
	v_pk_mul_f32 v[30:31], v[30:31], v[104:105]
	v_pk_mul_f32 v[26:27], v[26:27], v[108:109]
	v_pk_mul_f32 v[22:23], v[22:23], v[112:113]
	v_pk_mul_f32 v[18:19], v[18:19], v[116:117]
	v_pk_mul_f32 v[16:17], v[16:17], v[114:115]
